# attention: staging LDS addresses hoisted out of the tile loop, K/V source addresses via scalar row term, not-edge mask on SALU
# baseline (speedup 1.0000x reference)
; DEVI void attn_item(const P& p, int item, char* smem) {
;     const int tid = threadIdx.x, lane = tid & 63, w = tid >> 6, fr = lane & 15, fq = lane >> 4;
;     const int qt = item & 63, kvh = (item >> 6) & 3, b = item >> 8;
;     const int head = kvh * 4 + w, q0 = qt * 64;
;     const bf16_t* Q = (const bf16_t*)(p.ws + OFF_B) + ((size_t)(b * SEQ + q0)) * 1024 + head * 64;
;     const bf16_t* KB = (const bf16_t*)(p.ws + OFF_D);
;     const bf16_t* VT = (const bf16_t*)(p.ws + OFF_D + 17 * MiB);
;     char* sK = smem;
;     char* sV = smem + 8192;
;     const float sinkv = p.sink[head] * LOG2E;
;     const bf16_t* SGT = (const bf16_t*)(p.ws + OFF_C) + ((size_t)(b * SEQ + q0)) * 1024 + head * 64;
;     bf16_t* OG = (bf16_t*)(p.ws + OFF_A) + ((size_t)(b * SEQ + q0)) * 1024 + head * 64;
;     ...
;                 const int row = (tid >> 3) + 32 * i, ch = tid & 7;
;                 const uint4 kv = *(const uint4*)(KB + ((size_t)(b * TPB + tok0 + row)) * 256 + kvh * 64 + ch * 8);
;                 *(uint4*)(sK + row * 128 + ((ch ^ (row & 7)) << 4)) = kv;
;                 const uint4 vv = *(const uint4*)(VT + ((size_t)(b * 256 + kvh * 64 + row)) * TPB + tok0 + ch * 8);
;                 *(uint4*)(sV + row * 128 + ((ch ^ ((row >> 1) & 7)) << 4)) = vv;
.LBB0_1427:
	s_or_b64 exec, exec, s[2:3]
	s_cmpk_gt_i32 s86, 0x7ff
	s_barrier
	s_cbranch_scc1 .LBB0_1444
	v_xor_b32_e32 v4, v216, v172
	v_lshlrev_b32_e32 v4, 4, v4
	v_and_b32_e32 v4, 0x70, v4
	v_bfe_u32 v3, v172, 4, 2
	v_add_u32_e32 v123, 0, v4
	v_and_b32_e32 v4, 7, v172
	v_mov_b32_e32 v1, 0
	s_movk_i32 s2, 0x70
	v_and_b32_e32 v0, 0x70, v182
	v_and_b32_e32 v6, 14, v172
	v_bitop3_b32 v7, v175, v4, 3 bitop3:0x6c
	v_bitop3_b32 v4, v3, v4, 4 bitop3:0x36
	v_lshl_add_u64 v[98:99], s[54:55], 0, v[0:1]
	v_lshl_add_u64 v[100:101], s[0:1], 0, v[0:1]
	v_bitop3_b32 v0, v182, s2, v172 bitop3:0x48
	v_lshlrev_b32_e32 v125, 2, v3
	v_lshlrev_b32_e32 v8, 4, v4
	v_bitop3_b32 v4, v175, v6, 3 bitop3:0x6c
	v_add_u32_e32 v124, 0, v0
	v_sub_u32_e32 v0, v174, v125
	v_lshlrev_b32_e32 v9, 3, v4
	v_bitop3_b32 v4, v3, v6, 4 bitop3:0x36
	v_lshlrev_b32_e32 v2, 3, v3
	v_cmp_eq_u32_e32 vcc, 0, v3
	v_add_u32_e32 v126, 0x7f, v0
	v_lshrrev_b32_e32 v0, 2, v172
	v_lshlrev_b32_e32 v10, 3, v4
	v_bitop3_b32 v4, v3, v6, 8 bitop3:0x36
	v_bitop3_b32 v3, v3, v6, 12 bitop3:0x36
	v_lshl_add_u32 v5, v174, 7, 0
	v_and_b32_e32 v0, 8, v0
	v_add_u32_e32 v128, 32, v216
	v_lshlrev_b32_e32 v7, 4, v7
	v_lshlrev_b32_e32 v11, 3, v4
	v_lshlrev_b32_e32 v3, 3, v3
	v_and_b32_e32 v4, 16, v172
	s_mov_b32 s29, 0
	v_cndmask_b32_e64 v121, 0, 1.0, vcc
	v_lshlrev_b32_e32 v127, 7, v216
	v_lshlrev_b32_e32 v129, 7, v128
	s_lshl_b32 s34, s86, 6
	s_lshl_b32 s35, s27, 6
	v_lshlrev_b32_e32 v102, 1, v2
	v_mov_b32_e32 v103, v1
	v_lshlrev_b32_e32 v104, 1, v0
	v_mov_b32_e32 v105, v1
	s_movk_i32 s36, 0x2200
	v_lshlrev_b32_e32 v106, 1, v4
	v_mov_b32_e32 v107, v1
	v_add_u32_e32 v130, v5, v7
	v_add_u32_e32 v131, v5, v8
	s_movk_i32 s37, 0xfeff
	s_movk_i32 s38, 0x101
	s_movk_i32 s39, 0xfefe
	v_add_u32_e32 v132, v5, v9
	v_add_u32_e32 v133, v5, v10
	v_add_u32_e32 v134, v5, v11
	v_add_u32_e32 v135, v5, v3
	v_and_b32_e32 v2, 7, v172
	v_and_b32_e32 v3, 4, v2
	v_and_b32_e32 v4, 1, v2
	v_lshl_or_b32 v3, v4, 1, v3
	v_bfe_u32 v4, v216, 1, 3
	v_xor_b32_e32 v3, v3, v4
	v_bfe_u32 v4, v2, 1, 1
	v_lshlrev_b32_e32 v4, 3, v4
	v_lshl_or_b32 v124, v3, 4, v4
	v_xor_b32_e32 v228, 16, v124
	v_bfe_u32 v2, v172, 4, 2
	v_bfe_u32 v3, v174, 1, 3
	v_xor_b32_e32 v2, v2, v3
	v_lshl_add_u32 v132, v2, 4, v5
	v_xor_b32_e32 v134, 64, v132
	v_add_u32_e32 v133, v123, v127
	v_add_u32_e32 v135, v124, v127
	v_add_u32_e32 v217, v123, v129
	v_add_u32_e32 v229, v124, v129
	v_add_u32_e32 v214, v228, v127
	v_add_u32_e32 v215, v228, v129
	v_mov_b32_e32 v136, 0xf149f2ca
	s_mov_b32 s42, s86
	s_branch .LBB0_1430

; DEVI void attn_item(const P& p, int item, char* smem) {
;     const int tid = threadIdx.x, lane = tid & 63, w = tid >> 6, fr = lane & 15, fq = lane >> 4;
;     const int qt = item & 63, kvh = (item >> 6) & 3, b = item >> 8;
;     const int head = kvh * 4 + w, q0 = qt * 64;
;     const bf16_t* Q = (const bf16_t*)(p.ws + OFF_B) + ((size_t)(b * SEQ + q0)) * 1024 + head * 64;
;     const bf16_t* KB = (const bf16_t*)(p.ws + OFF_D);
;     const bf16_t* VT = (const bf16_t*)(p.ws + OFF_D + 17 * MiB);
;     char* sK = smem;
;     char* sV = smem + 8192;
;     const float sinkv = p.sink[head] * LOG2E;
;     const bf16_t* SGT = (const bf16_t*)(p.ws + OFF_C) + ((size_t)(b * SEQ + q0)) * 1024 + head * 64;
;     bf16_t* OG = (bf16_t*)(p.ws + OFF_A) + ((size_t)(b * SEQ + q0)) * 1024 + head * 64;
.LBB0_1430:
	s_bfe_u32 s6, s42, 0x20006
	v_lshl_add_u32 v0, s6, 2, v179
	v_lshlrev_b32_e32 v2, 2, v0
	global_load_dword v4, v2, s[84:85]
	s_ashr_i32 s46, s42, 8
	s_lshl_b32 s0, s42, 6
	s_and_b32 s1, s0, 0xfc0
	s_lshl_b32 s0, s46, 12
	s_or_b32 s0, s0, s1
	s_and_b32 s43, s34, 0xfc0
	v_add_u32_e32 v137, s1, v126
	s_ashr_i32 s1, s0, 31
	s_addk_i32 s43, 0x80
	s_lshl_b64 s[0:1], s[0:1], 11
	s_add_u32 s4, s80, s0
	v_lshlrev_b32_e32 v0, 7, v0
	s_addc_u32 s5, s81, s1
	v_lshl_add_u64 v[2:3], s[4:5], 0, v[0:1]
	s_add_u32 s4, s82, s0
	s_addc_u32 s5, s83, s1
	s_add_u32 s0, s90, s0
	v_lshl_add_u64 v[110:111], s[4:5], 0, v[0:1]
	s_addc_u32 s1, s91, s1
	s_lshl_b32 s4, s6, 6
	s_and_b32 s5, s42, 0xffffff00
	v_lshl_add_u64 v[108:109], v[2:3], 0, v[102:103]
	v_lshl_add_u64 v[2:3], s[0:1], 0, v[0:1]
	s_or_b32 s0, s4, s5
	s_lshl_b32 s28, s6, 7
	v_lshl_add_u64 v[2:3], v[2:3], 0, v[104:105]
	v_add_u32_e32 v0, s0, v216
	v_add_u32_e32 v5, s0, v128
	s_mov_b64 s[2:3], -1
	s_mulk_i32 s46, 0x1100
	v_lshl_add_u64 v[112:113], v[98:99], 0, s[28:29]
	v_lshlrev_b32_e32 v226, 9, v216
	v_mov_b32_e32 v227, 0
	v_lshl_add_u64 v[226:227], v[112:113], 0, v[226:227]
	v_mad_i64_i32 v[114:115], s[0:1], v0, s36, 0
	v_mad_i64_i32 v[116:117], s[0:1], v5, s36, 0
	v_lshl_add_u64 v[118:119], v[2:3], 0, v[106:107]
	s_mov_b32 s4, 0
	s_waitcnt vmcnt(0)
	v_mul_f32_e32 v138, 0x3fb8aa3b, v4
	s_branch .LBB0_1432

; DEVI void attn_item(const P& p, int item, char* smem) {
;     ...
;     for (int mh = 0; mh < 2; ++mh) {
;         const int mo = mh * 32;
;         bf16x8 Qf[2][2];
; #pragma unroll
;         for (int m = 0; m < 2; ++m)
; #pragma unroll
;             for (int kk = 0; kk < 2; ++kk) Qf[m][kk] = *(const bf16x8*)(Q + (size_t)(mo + 16 * m + fr) * 1024 + kk * 32 + fq * 8);
;         f32x4 O[4][2];
; #pragma unroll
;         for (int nd = 0; nd < 4; ++nd)
; #pragma unroll
;             for (int m = 0; m < 2; ++m) O[nd][m] = (f32x4){0.f, 0.f, 0.f, 0.f};
;         float mrow[2], lrow[2];
; #pragma unroll
;         for (int m = 0; m < 2; ++m) { mrow[m] = sinkv; lrow[m] = (fq == 0) ? 1.0f : 0.0f; }
;     ...
;                 const size_t off = (size_t)(mo + 16 * m + fr) * 1024 + 16 * nd + 4 * fq;
;                 const uint2 g = *(const uint2*)(SGT + off);
.LBB0_1432:
	v_or_b32_e32 v0, s4, v174
	v_lshlrev_b32_e32 v122, 10, v0
	v_lshlrev_b32_e32 v0, 11, v0
	v_or_b32_e32 v120, 0x4000, v122
	v_lshl_add_u64 v[2:3], v[108:109], 0, v[0:1]
	v_lshlrev_b32_e32 v0, 1, v120
	global_load_dwordx4 v[22:25], v[2:3], off
	global_load_dwordx4 v[26:29], v[2:3], off offset:64
	v_lshl_add_u64 v[2:3], v[108:109], 0, v[0:1]
	global_load_dwordx4 v[30:33], v[2:3], off
	global_load_dwordx4 v[34:37], v[2:3], off offset:64
	v_or_b32_e32 v50, v122, v125
	v_lshlrev_b32_e32 v50, 1, v50
	v_mov_b32_e32 v51, 0
	v_lshl_add_u64 v[52:53], v[110:111], 0, v[50:51]
	global_load_dwordx2 v[206:207], v[52:53], off
	global_load_dwordx2 v[208:209], v[52:53], off offset:32
	global_load_dwordx2 v[210:211], v[52:53], off offset:64
	global_load_dwordx2 v[212:213], v[52:53], off offset:96
	v_or_b32_e32 v50, v120, v125
	v_lshlrev_b32_e32 v50, 1, v50
	v_lshl_add_u64 v[52:53], v[110:111], 0, v[50:51]
	global_load_dwordx2 v[218:219], v[52:53], off
	global_load_dwordx2 v[220:221], v[52:53], off offset:32
	global_load_dwordx2 v[222:223], v[52:53], off offset:64
	global_load_dwordx2 v[224:225], v[52:53], off offset:96
	v_mov_b32_e32 v2, v1
	v_mov_b32_e32 v3, v1
	v_mov_b32_e32 v0, v1
	v_mov_b64_e32 v[40:41], v[2:3]
	v_mov_b64_e32 v[16:17], v[2:3]
	v_mov_b64_e32 v[44:45], v[2:3]
	v_mov_b64_e32 v[12:13], v[2:3]
	v_mov_b64_e32 v[48:49], v[2:3]
	v_mov_b64_e32 v[8:9], v[2:3]
	v_mov_b64_e32 v[20:21], v[2:3]
	v_add_u32_e32 v140, s4, v137
	v_mov_b64_e32 v[38:39], v[0:1]
	v_mov_b64_e32 v[14:15], v[0:1]
	v_mov_b64_e32 v[42:43], v[0:1]
	v_mov_b64_e32 v[10:11], v[0:1]
	v_mov_b64_e32 v[46:47], v[0:1]
	v_mov_b64_e32 v[6:7], v[0:1]
	v_mov_b64_e32 v[18:19], v[0:1]
	v_mov_b64_e32 v[4:5], v[2:3]
	s_xor_b64 s[0:1], s[2:3], -1
	v_add_u32_e32 v141, 16, v140
	v_add_u32_e32 v142, -2, v140
	v_add_u32_e32 v143, -3, v140
	v_add_u32_e32 v144, -16, v140
	v_subrev_u32_e32 v145, 17, v140
	v_subrev_u32_e32 v146, 18, v140
	v_subrev_u32_e32 v147, 19, v140
	v_subrev_u32_e32 v148, 32, v140
	v_subrev_u32_e32 v149, 33, v140
	v_subrev_u32_e32 v150, 34, v140
	v_subrev_u32_e32 v151, 35, v140
	v_subrev_u32_e32 v152, 48, v140
	v_subrev_u32_e32 v153, 49, v140
	v_subrev_u32_e32 v154, 50, v140
	v_subrev_u32_e32 v155, 51, v140
	v_add_u32_e32 v156, 14, v140
	v_add_u32_e32 v157, 13, v140
	s_mov_b32 s28, 0
	s_mov_b32 s99, 0
	s_mov_b32 s47, s43
	v_mov_b32_e32 v158, v121
	v_mov_b32_e32 v139, v121
	v_mov_b32_e32 v160, v138
	v_mov_b32_e32 v159, v138
	v_mov_b64_e32 v[2:3], v[0:1]
	s_branch .LBB0_1435

; DEVI void attn_item(const P& p, int item, char* smem) {
;     ...
;             if (ti < 5) { const int kb = q0 - 128 + 64 * ti; if (kb < 0 || kb >= SEQ) continue; tok0 = CTX + kb; lat = true; }
;             else { tok0 = (ti - 5) * 64; lat = false; }
;             __syncthreads();
; #pragma unroll
;             for (int i = 0; i < 2; ++i) {
;                 const int row = (tid >> 3) + 32 * i, ch = tid & 7;
;                 const uint4 kv = *(const uint4*)(KB + ((size_t)(b * TPB + tok0 + row)) * 256 + kvh * 64 + ch * 8);
;                 *(uint4*)(sK + row * 128 + ((ch ^ (row & 7)) << 4)) = kv;
;                 const uint4 vv = *(const uint4*)(VT + ((size_t)(b * 256 + kvh * 64 + row)) * TPB + tok0 + ch * 8);
;                 *(uint4*)(sV + row * 128 + ((ch ^ ((row >> 1) & 7)) << 4)) = vv;
;             }
;             __syncthreads();
;     ...
;                 if (lat && (ti == 0 || ti == 4)) {
;                     const int qpos = q0 + mo + 16 * m + fr, kb = tok0 - CTX;
; #pragma unroll
;                     for (int n = 0; n < 4; ++n)
; #pragma unroll
;                         for (int j = 0; j < 4; ++j) {
;                             const int dd = qpos - (kb + 16 * n + 4 * fq + j);
;                             if (dd > 128 || dd < -128) s[n][j] = -1e30f;
;                         }
.LBB0_1439:
	s_andn2_b64 vcc, exec, s[4:5]
	s_cbranch_vccnz .LBB0_1434
	s_ashr_i32 s31, s30, 31
	s_cmp_lg_u32 s99, 0
	s_cbranch_scc1 .Lat_have
	s_mov_b32 s101, 0
	v_lshl_add_u64 v[58:59], s[30:31], 1, v[100:101]
	v_lshl_add_u64 v[54:55], v[58:59], 0, v[114:115]
	v_lshl_add_u64 v[62:63], v[58:59], 0, v[116:117]
	s_add_i32 s100, s30, s46
	s_lshl_b32 s100, s100, 9
	v_lshl_add_u64 v[50:51], v[226:227], 0, s[100:101]
	s_add_i32 s100, s100, 0x4000
	v_lshl_add_u64 v[60:61], v[226:227], 0, s[100:101]
	global_load_dwordx4 v[190:193], v[50:51], off
	global_load_dwordx4 v[194:197], v[54:55], off
	global_load_dwordx4 v[198:201], v[60:61], off
	global_load_dwordx4 v[202:205], v[62:63], off
.Lat_have:
	s_barrier
	s_and_b32 s4, s28, 11
	s_cmp_eq_u32 s4, 0
	s_cselect_b64 s[18:19], -1, 0
	s_and_b64 s[18:19], s[2:3], s[18:19]
	s_andn2_b64 vcc, exec, s[18:19]
	s_andn2_b64 s[2:3], exec, s[18:19]
	s_cbranch_vccnz .Lat_noprep
	v_sub_u32_e32 v0, s30, v140
	v_subrev_u32_e32 v171, s30, v142
	v_subrev_u32_e32 v170, s30, v143
	v_subrev_u32_e32 v168, s30, v144
	v_subrev_u32_e32 v169, s30, v145
	v_subrev_u32_e32 v165, s30, v146
	v_subrev_u32_e32 v162, s30, v147
	v_subrev_u32_e32 v166, s30, v148
	v_subrev_u32_e32 v163, s30, v149
	v_subrev_u32_e32 v167, s30, v150
	v_subrev_u32_e32 v164, s30, v151
	v_subrev_u32_e32 v161, s30, v140
	v_cmp_gt_u32_e64 s[4:5], s38, v0
	v_cmp_lt_u32_e64 s[6:7], s39, v171
	v_cmp_lt_u32_e64 s[8:9], s39, v170
	v_cmp_lt_u32_e64 s[10:11], s39, v168
	v_cmp_lt_u32_e64 s[12:13], s39, v169
	v_cmp_lt_u32_e64 s[14:15], s39, v165
	v_cmp_lt_u32_e64 s[16:17], s39, v162
	v_cmp_lt_u32_e64 s[20:21], s39, v163
	v_cmp_lt_u32_e64 s[22:23], s39, v167
	v_cmp_lt_u32_e64 s[24:25], s39, v164
	v_cmp_lt_u32_e64 s[56:57], s39, v166
.Lat_noprep:
	s_waitcnt vmcnt(0)
	ds_write_b128 v133, v[190:193]
	ds_write_b64 v135, v[194:195] offset:8192
	ds_write_b64 v214, v[196:197] offset:8192
	ds_write_b128 v217, v[198:201]
	ds_write_b64 v229, v[202:203] offset:8192
	ds_write_b64 v215, v[204:205] offset:8192
	s_mov_b32 s99, 0
	s_cmp_lt_u32 s28, 8
	s_cbranch_scc0 .Lat_nopf
	s_cmp_gt_u32 s28, 3
	s_cbranch_scc1 .Lat_ctx
	s_add_i32 s100, s47, 64
	s_add_i32 s98, s100, 0xffffff00
	s_cmpk_lt_u32 s98, 0x1000
	s_cbranch_scc0 .Lat_nopf
	s_branch .Lat_issue

; DEVI void attn_item(const P& p, int item, char* smem) {
;     ...
;             for (int i = 0; i < 2; ++i) {
;                 const int row = (tid >> 3) + 32 * i, ch = tid & 7;
;                 const uint4 kv = *(const uint4*)(KB + ((size_t)(b * TPB + tok0 + row)) * 256 + kvh * 64 + ch * 8);
;                 *(uint4*)(sK + row * 128 + ((ch ^ (row & 7)) << 4)) = kv;
;                 const uint4 vv = *(const uint4*)(VT + ((size_t)(b * 256 + kvh * 64 + row)) * TPB + tok0 + ch * 8);
;                 *(uint4*)(sV + row * 128 + ((ch ^ ((row >> 1) & 7)) << 4)) = vv;
;             }
;             __syncthreads();
;             bf16x8 Kf[4][2];
; #pragma unroll
;             for (int n = 0; n < 4; ++n)
; #pragma unroll
;                 for (int kk = 0; kk < 2; ++kk) Kf[n][kk] = *(const bf16x8*)(sK + (16 * n + fr) * 128 + (((kk * 4 + fq) ^ (fr & 7)) << 4));
;             bf16x8 Pf[2][2];
; #pragma unroll
;             for (int m = 0; m < 2; ++m) {
;                 f32x4 s[4];
; #pragma unroll
;                 for (int n = 0; n < 4; ++n) {
;                     s[n] = (f32x4){0.f, 0.f, 0.f, 0.f};
; #pragma unroll
;                     for (int kk = 0; kk < 2; ++kk) s[n] = __builtin_amdgcn_mfma_f32_16x16x32_bf16(Kf[n][kk], Qf[m][kk], s[n], 0, 0, 0);
;                 }
;                 if (lat && (ti == 0 || ti == 4)) {
;                     const int qpos = q0 + mo + 16 * m + fr, kb = tok0 - CTX;
; #pragma unroll
;                     for (int n = 0; n < 4; ++n)
; #pragma unroll
;                         for (int j = 0; j < 4; ++j) {
;                             const int dd = qpos - (kb + 16 * n + 4 * fq + j);
;                             if (dd > 128 || dd < -128) s[n][j] = -1e30f;
;                         }
;                 }
.Lat_issue:
	s_mov_b32 s101, 0
	v_lshl_add_u64 v[58:59], s[100:101], 1, v[100:101]
	v_lshl_add_u64 v[54:55], v[58:59], 0, v[114:115]
	v_lshl_add_u64 v[62:63], v[58:59], 0, v[116:117]
	s_add_i32 s100, s100, s46
	s_lshl_b32 s100, s100, 9
	v_lshl_add_u64 v[50:51], v[226:227], 0, s[100:101]
	s_add_i32 s100, s100, 0x4000
	v_lshl_add_u64 v[60:61], v[226:227], 0, s[100:101]
	global_load_dwordx4 v[190:193], v[50:51], off
	global_load_dwordx4 v[194:197], v[54:55], off
	global_load_dwordx4 v[198:201], v[60:61], off
	global_load_dwordx4 v[202:205], v[62:63], off
	s_mov_b32 s99, 1
.Lat_nopf:
	s_waitcnt lgkmcnt(0)
	s_barrier
	ds_read_b128 v[70:73], v130
	ds_read_b128 v[62:65], v130 offset:2048
	ds_read_b128 v[54:57], v130 offset:4096
	ds_read_b128 v[82:85], v130 offset:6144
	ds_read_b128 v[94:97], v131
	ds_read_b128 v[90:93], v131 offset:2048
	ds_read_b128 v[86:89], v131 offset:4096
	ds_read_b128 v[66:69], v131 offset:6144
	s_waitcnt lgkmcnt(7)
	v_mfma_f32_16x16x32_bf16 v[50:53], v[70:73], v[22:25], 0
	s_waitcnt lgkmcnt(6)
	v_mfma_f32_16x16x32_bf16 v[58:61], v[62:65], v[22:25], 0
	s_waitcnt lgkmcnt(5)
	v_mfma_f32_16x16x32_bf16 v[182:185], v[54:57], v[22:25], 0
	s_waitcnt lgkmcnt(4)
	v_mfma_f32_16x16x32_bf16 v[186:189], v[82:85], v[22:25], 0
	s_waitcnt lgkmcnt(3)
	v_mfma_f32_16x16x32_bf16 v[78:81], v[94:97], v[26:29], v[50:53]
	s_waitcnt lgkmcnt(2)
	v_mfma_f32_16x16x32_bf16 v[74:77], v[90:93], v[26:29], v[58:61]
	s_waitcnt lgkmcnt(1)
	v_mfma_f32_16x16x32_bf16 v[58:61], v[86:89], v[26:29], v[182:185]
	s_waitcnt lgkmcnt(0)
	v_mfma_f32_16x16x32_bf16 v[50:53], v[66:69], v[26:29], v[186:189]
	s_cbranch_vccnz .LBB0_1442
	v_cmp_gt_u32_e32 vcc, s37, v161
	v_subrev_u32_e32 v173, s30, v152
	v_cndmask_b32_e64 v79, v136, v79, s[4:5]
	v_cndmask_b32_e32 v78, v78, v136, vcc
	v_cmp_lt_u32_e32 vcc, s39, v173
	v_subrev_u32_e32 v173, s30, v153
	v_cndmask_b32_e64 v80, v136, v80, s[6:7]
	v_cndmask_b32_e32 v50, v136, v50, vcc
	v_cmp_lt_u32_e32 vcc, s39, v173
	v_subrev_u32_e32 v173, s30, v154
	v_cndmask_b32_e64 v81, v136, v81, s[8:9]
	v_cndmask_b32_e32 v51, v136, v51, vcc
	v_cmp_lt_u32_e32 vcc, s39, v173
	v_subrev_u32_e32 v173, s30, v155
	v_cndmask_b32_e64 v74, v136, v74, s[10:11]
	v_cndmask_b32_e32 v52, v136, v52, vcc
	v_cmp_lt_u32_e32 vcc, s39, v173
	v_cndmask_b32_e64 v75, v136, v75, s[12:13]
	v_cndmask_b32_e64 v76, v136, v76, s[14:15]
	v_cndmask_b32_e64 v77, v136, v77, s[16:17]
	v_cndmask_b32_e64 v58, v136, v58, s[56:57]
	v_cndmask_b32_e64 v59, v136, v59, s[20:21]
	v_cndmask_b32_e64 v60, v136, v60, s[22:23]
	v_cndmask_b32_e64 v61, v136, v61, s[24:25]
	v_cndmask_b32_e32 v53, v136, v53, vcc
